# chunk attention live path: the clipped-distance bias entry is read from LDS once per item (kept in v142) instead of once per key tile with a full lgkmcnt(0) wait
# speedup vs baseline: 1.0022x; 1.0022x over previous
; DI int perm23(int i) { return (i & 0x13) | (((i >> 3) & 1) << 2) | (((i >> 2) & 1) << 3); }
; DI f32x16 zero16() { f32x16 z; for (int i = 0; i < 16; ++i) z[i] = 0.f; return z; }
; DI void attn_item(const Params& p, char* lds, int item) {
;     ...
;   const int pi = perm23(l31);
;   const int sr = tid >> 3, sc8 = (tid & 7) * 8;
;   const u16* kg = PA + ((size_t)b * SEQ + sr) * 1024 + 512 + h * 64 + sc8;
;   const u16* vg = VTa + ((size_t)((b * 8 + h) * 64 + sr)) * SEQ + sc8;
;   for (int i = tid; i < 257; i += 512) biasl[i] = p.in[10][h * 257 + i] * 1.4426950408889634f;
;   const size_t q0 = (size_t)b * SEQ + qc * 64 + qt * 32;
;   bf16x8 Qf[4];
; #pragma unroll
;   for (int kk = 0; kk < 4; ++kk) Qf[kk] = ldfrag(PA + (q0 + l31) * 1024 + h * 64 + kk * 16 + 8 * hh);
;   const int kcs = (c0 >= 8) ? c0 - 8 : 0, kce = c0 + 3;
;   *(uint4*)(Kl + sr * 72 + sc8) = *(const uint4*)(kg + (size_t)(kcs * 64) * 1024);
;   *(uint4*)(Vl + sr * 72 + sc8) = *(const uint4*)(vg + kcs * 64);
;   __syncthreads();
;   f32x16 O[2]; O[0] = zero16(); O[1] = zero16();
;   float mrun = -INFINITY, lrun = 0.f;
.LBB0_393:
	s_or_b64 exec, exec, s[0:1]
	s_bfe_u32 s1, s15, 0x50002
	s_lshl_b32 s0, s1, 2
	s_min_u32 s0, s0, 8
	v_lshrrev_b32_e32 v11, 1, v2
	v_lshlrev_b32_e32 v4, 1, v2
	s_lshl_b32 s1, s1, 8
	s_lshl_b32 s16, s0, 6
	v_and_b32_e32 v0, 19, v2
	v_and_b32_e32 v3, 4, v11
	v_and_b32_e32 v4, 8, v4
	s_lshl_b32 s23, s6, 6
	s_sub_i32 s22, s1, s16
	v_or3_b32 v12, v0, v3, v4
	v_ashrrev_i32_e32 v4, 3, v2
	s_add_i32 s16, s23, s13
	v_and_b32_e32 v8, 31, v2
	v_bfe_u32 v9, v2, 5, 1
	v_ashrrev_i32_e32 v10, 7, v2
	v_lshlrev_b32_e32 v0, 4, v2
	v_add_u32_e32 v2, s16, v4
	s_lshl_b32 s1, s75, 2
	v_ashrrev_i32_e32 v3, 31, v2
	s_and_b32 s1, s1, 0x7c
	v_lshlrev_b64 v[2:3], 14, v[2:3]
	v_add_u32_e32 v81, s1, v10
	v_and_b32_e32 v0, 0x70, v0
	v_lshl_add_u64 v[2:3], s[10:11], 0, v[2:3]
	v_lshl_add_u64 v[86:87], v[2:3], 0, v[0:1]
	v_lshlrev_b32_e32 v2, 6, v81
	v_ashrrev_i32_e32 v5, 31, v4
	v_ashrrev_i32_e32 v3, 31, v2
	v_lshl_add_u64 v[6:7], v[4:5], 0, s[4:5]
	v_readlane_b32 s18, v250, 8
	v_lshl_add_u64 v[2:3], v[2:3], 0, s[4:5]
	v_and_b32_e32 v11, 32, v11
	v_lshlrev_b64 v[6:7], 11, v[6:7]
	v_readlane_b32 s19, v250, 9
	v_or3_b32 v2, v2, v11, v8
	s_lshl_b32 s6, s6, 7
	v_lshl_add_u64 v[6:7], s[18:19], 0, v[6:7]
	v_lshlrev_b64 v[84:85], 11, v[2:3]
	v_lshl_add_u64 v[6:7], v[6:7], 0, s[6:7]
	v_lshl_add_u64 v[2:3], s[18:19], 0, v[84:85]
	v_lshl_add_u64 v[82:83], v[6:7], 0, v[0:1]
	v_lshl_add_u64 v[2:3], v[2:3], 0, s[6:7]
	v_lshlrev_b32_e32 v6, 4, v9
	v_mov_b32_e32 v7, v1
	v_lshl_add_u64 v[2:3], v[2:3], 0, v[6:7]
	v_sub_u32_e64 v7, s1, 8 clamp
	global_load_dwordx4 v[64:67], v[2:3], off
	global_load_dwordx4 v[68:71], v[2:3], off offset:32
	global_load_dwordx4 v[72:75], v[2:3], off offset:64
	global_load_dwordx4 v[76:79], v[2:3], off offset:96
	v_lshlrev_b32_e32 v2, 17, v7
	v_mov_b32_e32 v3, v1
	v_lshl_add_u64 v[2:3], v[82:83], 0, v[2:3]
	v_mul_lo_u32 v4, v4, s34
	v_add3_u32 v131, 0, v4, v0
	global_load_dwordx4 v[2:5], v[2:3], off offset:1024
	v_lshlrev_b32_e32 v0, 7, v7
	v_lshl_add_u64 v[144:145], v[86:87], 0, v[0:1]
	global_load_dwordx4 v[140:143], v[144:145], off
	v_lshlrev_b32_e32 v80, 3, v9
	v_mov_b32_e32 v14, v1
	v_mov_b32_e32 v15, v1
	v_readfirstlane_b32 s26, v7
	v_mov_b32_e32 v7, v1
	v_mov_b32_e32 v9, v1
	v_mov_b32_e32 v13, v1
	s_or_b32 s27, s1, 3
	v_add_u32_e32 v132, -8, v81
	s_mov_b32 s76, 0
	v_mov_b32_e32 v138, 0xff800000
	v_mov_b32_e32 v137, 0
	s_waitcnt vmcnt(1)
	ds_write_b128 v131, v[2:5]
	v_add_u32_e32 v0, 0, v6
	v_mad_u32_u24 v133, v8, s34, v0
	v_mad_u32_u24 v134, v12, s34, v0
	v_sub_u32_e32 v0, v80, v8
	v_sub_u32_e32 v0, v0, v11
	v_mov_b32_e32 v6, v1
	v_mov_b32_e32 v8, v1
	v_mov_b32_e32 v12, v1
	s_waitcnt vmcnt(0)
	ds_write_b128 v131, v[140:143] offset:18432
	v_add_lshl_u32 v2, v10, s0, 6
	v_sub_u32_e32 v135, v0, v2
	v_or_b32_e32 v0, v11, v2
	v_sub_u32_e32 v136, 0, v0
	v_mov_b32_e32 v0, v1
	v_mov_b32_e32 v2, v1
	v_mov_b32_e32 v3, v1
	v_mov_b32_e32 v4, v1
	v_mov_b32_e32 v5, v1
	v_mov_b32_e32 v10, v1
	v_mov_b32_e32 v11, v1
	v_mov_b64_e32 v[30:31], v[14:15]
	v_mov_b64_e32 v[46:47], v[14:15]
	v_mov_b64_e32 v[28:29], v[12:13]
	v_mov_b64_e32 v[26:27], v[10:11]
	v_mov_b64_e32 v[24:25], v[8:9]
	v_mov_b64_e32 v[22:23], v[6:7]
	v_mov_b64_e32 v[20:21], v[4:5]
	v_mov_b64_e32 v[18:19], v[2:3]
	v_mov_b64_e32 v[16:17], v[0:1]
	v_mov_b64_e32 v[44:45], v[12:13]
	v_mov_b64_e32 v[42:43], v[10:11]
	v_mov_b64_e32 v[40:41], v[8:9]
	v_mov_b64_e32 v[38:39], v[6:7]
	v_mov_b64_e32 v[36:37], v[4:5]
	v_mov_b64_e32 v[34:35], v[2:3]
	v_mov_b64_e32 v[32:33], v[0:1]
	s_waitcnt lgkmcnt(0)
	s_barrier
	ds_read_b32 v142, v1 offset:36864
	s_waitcnt lgkmcnt(0)
	s_branch .LBB0_395

; DI void attn_item(const Params& p, char* lds, int item) {
;     ...
;         if ((kc * 64 + sub * 32 + 31) - (qc * 64 + qt * 32) <= -128) {
;           const float b0 = biasl[0];
; #pragma unroll
;           for (int r = 0; r < 16; ++r) { const float sv = S[sub][r] * 0.18033688011112042f + b0; S[sub][r] = sv; mx = fmaxf(mx, sv); }
.LBB0_400:
	s_andn2_saveexec_b64 s[16:17], s[16:17]
	s_cbranch_execz .LBB0_402
	v_mov_b32_e32 v14, v142
	s_nop 7
	v_pk_fma_f32 v[92:93], v[48:49], s[14:15], v[14:15] op_sel_hi:[1,0,0]
	v_pk_fma_f32 v[88:89], v[50:51], s[14:15], v[14:15] op_sel_hi:[1,0,0]
	v_pk_fma_f32 v[12:13], v[52:53], s[14:15], v[14:15] op_sel_hi:[1,0,0]
	v_pk_fma_f32 v[10:11], v[54:55], s[14:15], v[14:15] op_sel_hi:[1,0,0]
	v_pk_fma_f32 v[96:97], v[56:57], s[14:15], v[14:15] op_sel_hi:[1,0,0]
	v_max3_f32 v15, v92, s48, v93
	v_max3_f32 v15, v15, v88, v89
	v_max3_f32 v15, v15, v12, v13
	v_max3_f32 v15, v15, v10, v11
	v_max3_f32 v15, v15, v96, v97
	v_pk_fma_f32 v[94:95], v[58:59], s[14:15], v[14:15] op_sel_hi:[1,0,0]
	s_nop 0
	v_max3_f32 v15, v15, v94, v95
	v_pk_fma_f32 v[90:91], v[60:61], s[14:15], v[14:15] op_sel_hi:[1,0,0]
	s_nop 0
	v_max3_f32 v48, v15, v90, v91
	v_pk_fma_f32 v[14:15], v[62:63], s[14:15], v[14:15] op_sel_hi:[1,0,0]
	s_nop 0
	v_max3_f32 v139, v48, v14, v15

; DI void attn_item(const Params& p, char* lds, int item) {
;     ...
;         if ((kc * 64 + sub * 32 + 31) - (qc * 64 + qt * 32) <= -128) {
;           const float b0 = biasl[0];
; #pragma unroll
;           for (int r = 0; r < 16; ++r) { const float sv = S[sub][r] * 0.18033688011112042f + b0; S[sub][r] = sv; mx = fmaxf(mx, sv); }
.LBB0_404:
	s_andn2_saveexec_b64 s[16:17], s[16:17]
	s_cbranch_execz .LBB0_406
	v_mov_b32_e32 v0, v142
	s_nop 7
	v_pk_fma_f32 v[98:99], v[48:49], s[14:15], v[0:1] op_sel_hi:[1,0,0]
	v_pk_fma_f32 v[100:101], v[50:51], s[14:15], v[0:1] op_sel_hi:[1,0,0]
	v_max3_f32 v48, v139, v98, v99
	v_pk_fma_f32 v[102:103], v[52:53], s[14:15], v[0:1] op_sel_hi:[1,0,0]
	v_max3_f32 v48, v48, v100, v101
	v_pk_fma_f32 v[104:105], v[54:55], s[14:15], v[0:1] op_sel_hi:[1,0,0]
	v_max3_f32 v48, v48, v102, v103
	v_pk_fma_f32 v[106:107], v[56:57], s[14:15], v[0:1] op_sel_hi:[1,0,0]
	v_max3_f32 v48, v48, v104, v105
	v_max3_f32 v48, v48, v106, v107
	v_pk_fma_f32 v[108:109], v[58:59], s[14:15], v[0:1] op_sel_hi:[1,0,0]
	v_pk_fma_f32 v[110:111], v[60:61], s[14:15], v[0:1] op_sel_hi:[1,0,0]
	v_max3_f32 v48, v48, v108, v109
	v_max3_f32 v48, v48, v110, v111
	v_pk_fma_f32 v[112:113], v[62:63], s[14:15], v[0:1] op_sel_hi:[1,0,0]
	s_nop 0
	v_max3_f32 v0, v48, v112, v113
